# baseline (speedup 1.0000x reference)
; __global__ void __launch_bounds__(NTHREADS, 2) fwd_megakernel(Params p_arg) {
;     ...
;   if (xb.local_ok) {
; #pragma unroll 1
;     for (int i = 0; i < (int)xb.x * XCC_SKEW_SLEEPS; ++i) __builtin_amdgcn_s_sleep(127);
;   }
.LBB0_110:
	s_or_b64 exec, exec, s[4:5]
	s_cmpk_gt_u32 s16, 0xffff
	s_cselect_b64 s[4:5], -1, 0
	s_cmp_gt_i32 s7, 0
	s_cselect_b64 s[0:1], -1, 0
	v_writelane_b32 v255, s4, 16
	s_and_b64 s[0:1], s[4:5], s[0:1]
	s_mov_b32 s29, 0
	v_writelane_b32 v255, s5, 17
	s_and_b64 vcc, exec, s[0:1]
	s_barrier
	s_cbranch_vccz .LBB0_113
	s_lshl_b32 s0, s7, 1
	s_add_i32 s0, s0, -1
	s_cmp_lt_i32 s0, 1
	s_cbranch_scc1 .LBB0_113
